# neighbourhood attention: batched branch-free bias add/mask instead of 32 exec-masked waited LDS loads per tile
# speedup vs baseline: 1.0183x; 1.0076x over previous
; DI int crow(int r, int h) { return (r & 3) + 8 * (r >> 2) + 4 * h; }
; DI void attn_item(const Params& p, int layer, int item, char* smem) {
;     ...
;       if (tile < 64 && maskmode == 1) {
;         int qr = tq >> 6, qc = tq & 63;
;         int ws = min(max(qc - 8, 0), 48);
;         int dr = tile - qr + 7;
; #pragma unroll
;         for (int kt = 0; kt < 2; ++kt)
; #pragma unroll
;           for (int r = 0; r < 16; ++r) {
;             int kc = kt * 32 + crow(r, h);
;             bool ok = (unsigned)(kc - ws) < 16u;
;             int bi = ok ? (dr * 31 + kc - qc + 15) : 0;
;             float bv = s_rpb[bi];
;             S[kt][r] = ok ? (S[kt][r] + bv) : -INFINITY;
;           }
.LBB0_314:
	s_andn2_b64 vcc, exec, s[4:5]
	s_cbranch_vccnz .LBB0_382
	s_cmp_eq_u32 s18, 1
	s_cbranch_scc0 .LBB0_381
	v_sub_u32_e32 v112, s24, v188
	v_mul_lo_u32 v112, v112, 31
	v_sub_u32_e32 v112, v112, v194
	v_lshl_add_u32 v198, v112, 2, v191
	ds_read_b32 v116, v198 offset:37792
	ds_read_b32 v117, v198 offset:37796
	ds_read_b32 v118, v198 offset:37800
	ds_read_b32 v119, v198 offset:37804
	ds_read_b32 v120, v198 offset:37824
	ds_read_b32 v121, v198 offset:37828
	ds_read_b32 v122, v198 offset:37832
	ds_read_b32 v123, v198 offset:37836
	ds_read_b32 v124, v198 offset:37856
	ds_read_b32 v125, v198 offset:37860
	ds_read_b32 v126, v198 offset:37864
	ds_read_b32 v127, v198 offset:37868
	ds_read_b32 v128, v198 offset:37888
	ds_read_b32 v129, v198 offset:37892
	ds_read_b32 v130, v198 offset:37896
	ds_read_b32 v131, v198 offset:37900
	v_sub_u32_e64 v113, v194, 8 clamp
	v_min_u32_e32 v113, 48, v113
	v_mbcnt_lo_u32_b32 v114, -1, 0
	v_mbcnt_hi_u32_b32 v114, -1, v114
	v_lshrrev_b32_e32 v114, 3, v114
	v_and_b32_e32 v114, 4, v114
	v_sub_u32_e32 v113, v113, v114
	v_mov_b32_e32 v115, 0xff800000
	v_sub_u32_e32 v112, 0, v113
	s_waitcnt lgkmcnt(12)
	v_cmp_gt_u32_e32 vcc, 16, v112
	v_sub_u32_e32 v114, 1, v113
	v_add_f32_e32 v96, v96, v116
	v_cndmask_b32_e32 v96, v115, v96, vcc
	v_cmp_gt_u32_e32 vcc, 16, v114
	v_sub_u32_e32 v112, 2, v113
	v_add_f32_e32 v97, v97, v117
	v_cndmask_b32_e32 v97, v115, v97, vcc
	v_cmp_gt_u32_e32 vcc, 16, v112
	v_sub_u32_e32 v114, 3, v113
	v_add_f32_e32 v98, v98, v118
	v_cndmask_b32_e32 v98, v115, v98, vcc
	v_cmp_gt_u32_e32 vcc, 16, v114
	v_sub_u32_e32 v112, 8, v113
	v_add_f32_e32 v99, v99, v119
	v_cndmask_b32_e32 v99, v115, v99, vcc
	s_waitcnt lgkmcnt(8)
	v_cmp_gt_u32_e32 vcc, 16, v112
	v_sub_u32_e32 v114, 9, v113
	v_add_f32_e32 v100, v100, v120
	v_cndmask_b32_e32 v100, v115, v100, vcc
	v_cmp_gt_u32_e32 vcc, 16, v114
	v_sub_u32_e32 v112, 10, v113
	v_add_f32_e32 v101, v101, v121
	v_cndmask_b32_e32 v101, v115, v101, vcc
	v_cmp_gt_u32_e32 vcc, 16, v112
	v_sub_u32_e32 v114, 11, v113
	v_add_f32_e32 v102, v102, v122
	v_cndmask_b32_e32 v102, v115, v102, vcc
	v_cmp_gt_u32_e32 vcc, 16, v114
	v_sub_u32_e32 v112, 16, v113
	v_add_f32_e32 v103, v103, v123
	v_cndmask_b32_e32 v103, v115, v103, vcc
	s_waitcnt lgkmcnt(4)
	v_cmp_gt_u32_e32 vcc, 16, v112
	v_sub_u32_e32 v114, 17, v113
	v_add_f32_e32 v104, v104, v124
	v_cndmask_b32_e32 v104, v115, v104, vcc
	v_cmp_gt_u32_e32 vcc, 16, v114
	v_sub_u32_e32 v112, 18, v113
	v_add_f32_e32 v105, v105, v125
	v_cndmask_b32_e32 v105, v115, v105, vcc
	v_cmp_gt_u32_e32 vcc, 16, v112
	v_sub_u32_e32 v114, 19, v113
	v_add_f32_e32 v106, v106, v126
	v_cndmask_b32_e32 v106, v115, v106, vcc
	v_cmp_gt_u32_e32 vcc, 16, v114
	v_sub_u32_e32 v112, 24, v113
	v_add_f32_e32 v107, v107, v127
	v_cndmask_b32_e32 v107, v115, v107, vcc
	s_waitcnt lgkmcnt(0)
	v_cmp_gt_u32_e32 vcc, 16, v112
	v_sub_u32_e32 v114, 25, v113
	v_add_f32_e32 v108, v108, v128
	v_cndmask_b32_e32 v108, v115, v108, vcc
	v_cmp_gt_u32_e32 vcc, 16, v114
	v_sub_u32_e32 v112, 26, v113
	v_add_f32_e32 v109, v109, v129
	v_cndmask_b32_e32 v109, v115, v109, vcc
	v_cmp_gt_u32_e32 vcc, 16, v112
	v_sub_u32_e32 v114, 27, v113
	v_add_f32_e32 v110, v110, v130
	v_cndmask_b32_e32 v110, v115, v110, vcc
	v_cmp_gt_u32_e32 vcc, 16, v114
	s_nop 0
	v_add_f32_e32 v111, v111, v131
	v_cndmask_b32_e32 v111, v115, v111, vcc
	ds_read_b32 v116, v198 offset:37920
	ds_read_b32 v117, v198 offset:37924
	ds_read_b32 v118, v198 offset:37928
	ds_read_b32 v119, v198 offset:37932
	ds_read_b32 v120, v198 offset:37952
	ds_read_b32 v121, v198 offset:37956
	ds_read_b32 v122, v198 offset:37960
	ds_read_b32 v123, v198 offset:37964
	ds_read_b32 v124, v198 offset:37984
	ds_read_b32 v125, v198 offset:37988
	ds_read_b32 v126, v198 offset:37992
	ds_read_b32 v127, v198 offset:37996
	ds_read_b32 v128, v198 offset:38016
	ds_read_b32 v129, v198 offset:38020
	ds_read_b32 v130, v198 offset:38024
	ds_read_b32 v131, v198 offset:38028
	v_sub_u32_e32 v112, 32, v113
	s_waitcnt lgkmcnt(12)
	v_cmp_gt_u32_e32 vcc, 16, v112
	v_sub_u32_e32 v114, 33, v113
	v_add_f32_e32 v80, v80, v116
	v_cndmask_b32_e32 v80, v115, v80, vcc
	v_cmp_gt_u32_e32 vcc, 16, v114
	v_sub_u32_e32 v112, 34, v113
	v_add_f32_e32 v81, v81, v117
	v_cndmask_b32_e32 v81, v115, v81, vcc
	v_cmp_gt_u32_e32 vcc, 16, v112
	v_sub_u32_e32 v114, 35, v113
	v_add_f32_e32 v82, v82, v118
	v_cndmask_b32_e32 v82, v115, v82, vcc
	v_cmp_gt_u32_e32 vcc, 16, v114
	v_sub_u32_e32 v112, 40, v113
	v_add_f32_e32 v83, v83, v119
	v_cndmask_b32_e32 v83, v115, v83, vcc
	s_waitcnt lgkmcnt(8)
	v_cmp_gt_u32_e32 vcc, 16, v112
	v_sub_u32_e32 v114, 41, v113
	v_add_f32_e32 v84, v84, v120
	v_cndmask_b32_e32 v84, v115, v84, vcc
	v_cmp_gt_u32_e32 vcc, 16, v114
	v_sub_u32_e32 v112, 42, v113
	v_add_f32_e32 v85, v85, v121
	v_cndmask_b32_e32 v85, v115, v85, vcc
	v_cmp_gt_u32_e32 vcc, 16, v112
	v_sub_u32_e32 v114, 43, v113
	v_add_f32_e32 v86, v86, v122
	v_cndmask_b32_e32 v86, v115, v86, vcc
	v_cmp_gt_u32_e32 vcc, 16, v114
	v_sub_u32_e32 v112, 48, v113
	v_add_f32_e32 v87, v87, v123
	v_cndmask_b32_e32 v87, v115, v87, vcc
	s_waitcnt lgkmcnt(4)
	v_cmp_gt_u32_e32 vcc, 16, v112
	v_sub_u32_e32 v114, 49, v113
	v_add_f32_e32 v88, v88, v124
	v_cndmask_b32_e32 v88, v115, v88, vcc
	v_cmp_gt_u32_e32 vcc, 16, v114
	v_sub_u32_e32 v112, 50, v113
	v_add_f32_e32 v89, v89, v125
	v_cndmask_b32_e32 v89, v115, v89, vcc
	v_cmp_gt_u32_e32 vcc, 16, v112
	v_sub_u32_e32 v114, 51, v113
	v_add_f32_e32 v90, v90, v126
	v_cndmask_b32_e32 v90, v115, v90, vcc
	v_cmp_gt_u32_e32 vcc, 16, v114
	v_sub_u32_e32 v112, 56, v113
	v_add_f32_e32 v91, v91, v127
	v_cndmask_b32_e32 v91, v115, v91, vcc
	s_waitcnt lgkmcnt(0)
	v_cmp_gt_u32_e32 vcc, 16, v112
	v_sub_u32_e32 v114, 57, v113
	v_add_f32_e32 v92, v92, v128
	v_cndmask_b32_e32 v92, v115, v92, vcc
	v_cmp_gt_u32_e32 vcc, 16, v114
	v_sub_u32_e32 v112, 58, v113
	v_add_f32_e32 v93, v93, v129
	v_cndmask_b32_e32 v93, v115, v93, vcc
	v_cmp_gt_u32_e32 vcc, 16, v112
	v_sub_u32_e32 v114, 59, v113
	v_add_f32_e32 v94, v94, v130
	v_cndmask_b32_e32 v94, v115, v94, vcc
	v_cmp_gt_u32_e32 vcc, 16, v114
	s_nop 0
	v_add_f32_e32 v95, v95, v131
	v_cndmask_b32_e32 v95, v115, v95, vcc
	s_branch .LBB0_383

; DI int crow(int r, int h) { return (r & 3) + 8 * (r >> 2) + 4 * h; }
; DI void attn_item(const Params& p, int layer, int item, char* smem) {
;     ...
;       if (tile < 64 && maskmode == 1) {
;         int qr = tq >> 6, qc = tq & 63;
;         int ws = min(max(qc - 8, 0), 48);
;         int dr = tile - qr + 7;
; #pragma unroll
;         for (int kt = 0; kt < 2; ++kt)
; #pragma unroll
;           for (int r = 0; r < 16; ++r) {
;             int kc = kt * 32 + crow(r, h);
;             bool ok = (unsigned)(kc - ws) < 16u;
;             int bi = ok ? (dr * 31 + kc - qc + 15) : 0;
;             float bv = s_rpb[bi];
;             S[kt][r] = ok ? (S[kt][r] + bv) : -INFINITY;
;           }
.LBB0_406:
	s_andn2_b64 vcc, exec, s[4:5]
	s_cbranch_vccnz .LBB0_474
	s_cmp_eq_u32 s18, 1
	s_cbranch_scc0 .LBB0_473
	v_sub_u32_e32 v112, s22, v188
	v_mul_lo_u32 v112, v112, 31
	v_sub_u32_e32 v112, v112, v194
	v_lshl_add_u32 v198, v112, 2, v191
	ds_read_b32 v116, v198 offset:37792
	ds_read_b32 v117, v198 offset:37796
	ds_read_b32 v118, v198 offset:37800
	ds_read_b32 v119, v198 offset:37804
	ds_read_b32 v120, v198 offset:37824
	ds_read_b32 v121, v198 offset:37828
	ds_read_b32 v122, v198 offset:37832
	ds_read_b32 v123, v198 offset:37836
	ds_read_b32 v124, v198 offset:37856
	ds_read_b32 v125, v198 offset:37860
	ds_read_b32 v126, v198 offset:37864
	ds_read_b32 v127, v198 offset:37868
	ds_read_b32 v128, v198 offset:37888
	ds_read_b32 v129, v198 offset:37892
	ds_read_b32 v130, v198 offset:37896
	ds_read_b32 v131, v198 offset:37900
	v_sub_u32_e64 v113, v194, 8 clamp
	v_min_u32_e32 v113, 48, v113
	v_mbcnt_lo_u32_b32 v114, -1, 0
	v_mbcnt_hi_u32_b32 v114, -1, v114
	v_lshrrev_b32_e32 v114, 3, v114
	v_and_b32_e32 v114, 4, v114
	v_sub_u32_e32 v113, v113, v114
	v_mov_b32_e32 v115, 0xff800000
	v_sub_u32_e32 v112, 0, v113
	s_waitcnt lgkmcnt(12)
	v_cmp_gt_u32_e32 vcc, 16, v112
	v_sub_u32_e32 v114, 1, v113
	v_add_f32_e32 v96, v96, v116
	v_cndmask_b32_e32 v96, v115, v96, vcc
	v_cmp_gt_u32_e32 vcc, 16, v114
	v_sub_u32_e32 v112, 2, v113
	v_add_f32_e32 v97, v97, v117
	v_cndmask_b32_e32 v97, v115, v97, vcc
	v_cmp_gt_u32_e32 vcc, 16, v112
	v_sub_u32_e32 v114, 3, v113
	v_add_f32_e32 v98, v98, v118
	v_cndmask_b32_e32 v98, v115, v98, vcc
	v_cmp_gt_u32_e32 vcc, 16, v114
	v_sub_u32_e32 v112, 8, v113
	v_add_f32_e32 v99, v99, v119
	v_cndmask_b32_e32 v99, v115, v99, vcc
	s_waitcnt lgkmcnt(8)
	v_cmp_gt_u32_e32 vcc, 16, v112
	v_sub_u32_e32 v114, 9, v113
	v_add_f32_e32 v100, v100, v120
	v_cndmask_b32_e32 v100, v115, v100, vcc
	v_cmp_gt_u32_e32 vcc, 16, v114
	v_sub_u32_e32 v112, 10, v113
	v_add_f32_e32 v101, v101, v121
	v_cndmask_b32_e32 v101, v115, v101, vcc
	v_cmp_gt_u32_e32 vcc, 16, v112
	v_sub_u32_e32 v114, 11, v113
	v_add_f32_e32 v102, v102, v122
	v_cndmask_b32_e32 v102, v115, v102, vcc
	v_cmp_gt_u32_e32 vcc, 16, v114
	v_sub_u32_e32 v112, 16, v113
	v_add_f32_e32 v103, v103, v123
	v_cndmask_b32_e32 v103, v115, v103, vcc
	s_waitcnt lgkmcnt(4)
	v_cmp_gt_u32_e32 vcc, 16, v112
	v_sub_u32_e32 v114, 17, v113
	v_add_f32_e32 v104, v104, v124
	v_cndmask_b32_e32 v104, v115, v104, vcc
	v_cmp_gt_u32_e32 vcc, 16, v114
	v_sub_u32_e32 v112, 18, v113
	v_add_f32_e32 v105, v105, v125
	v_cndmask_b32_e32 v105, v115, v105, vcc
	v_cmp_gt_u32_e32 vcc, 16, v112
	v_sub_u32_e32 v114, 19, v113
	v_add_f32_e32 v106, v106, v126
	v_cndmask_b32_e32 v106, v115, v106, vcc
	v_cmp_gt_u32_e32 vcc, 16, v114
	v_sub_u32_e32 v112, 24, v113
	v_add_f32_e32 v107, v107, v127
	v_cndmask_b32_e32 v107, v115, v107, vcc
	s_waitcnt lgkmcnt(0)
	v_cmp_gt_u32_e32 vcc, 16, v112
	v_sub_u32_e32 v114, 25, v113
	v_add_f32_e32 v108, v108, v128
	v_cndmask_b32_e32 v108, v115, v108, vcc
	v_cmp_gt_u32_e32 vcc, 16, v114
	v_sub_u32_e32 v112, 26, v113
	v_add_f32_e32 v109, v109, v129
	v_cndmask_b32_e32 v109, v115, v109, vcc
	v_cmp_gt_u32_e32 vcc, 16, v112
	v_sub_u32_e32 v114, 27, v113
	v_add_f32_e32 v110, v110, v130
	v_cndmask_b32_e32 v110, v115, v110, vcc
	v_cmp_gt_u32_e32 vcc, 16, v114
	s_nop 0
	v_add_f32_e32 v111, v111, v131
	v_cndmask_b32_e32 v111, v115, v111, vcc
	ds_read_b32 v116, v198 offset:37920
	ds_read_b32 v117, v198 offset:37924
	ds_read_b32 v118, v198 offset:37928
	ds_read_b32 v119, v198 offset:37932
	ds_read_b32 v120, v198 offset:37952
	ds_read_b32 v121, v198 offset:37956
	ds_read_b32 v122, v198 offset:37960
	ds_read_b32 v123, v198 offset:37964
	ds_read_b32 v124, v198 offset:37984
	ds_read_b32 v125, v198 offset:37988
	ds_read_b32 v126, v198 offset:37992
	ds_read_b32 v127, v198 offset:37996
	ds_read_b32 v128, v198 offset:38016
	ds_read_b32 v129, v198 offset:38020
	ds_read_b32 v130, v198 offset:38024
	ds_read_b32 v131, v198 offset:38028
	v_sub_u32_e32 v112, 32, v113
	s_waitcnt lgkmcnt(12)
	v_cmp_gt_u32_e32 vcc, 16, v112
	v_sub_u32_e32 v114, 33, v113
	v_add_f32_e32 v80, v80, v116
	v_cndmask_b32_e32 v80, v115, v80, vcc
	v_cmp_gt_u32_e32 vcc, 16, v114
	v_sub_u32_e32 v112, 34, v113
	v_add_f32_e32 v81, v81, v117
	v_cndmask_b32_e32 v81, v115, v81, vcc
	v_cmp_gt_u32_e32 vcc, 16, v112
	v_sub_u32_e32 v114, 35, v113
	v_add_f32_e32 v82, v82, v118
	v_cndmask_b32_e32 v82, v115, v82, vcc
	v_cmp_gt_u32_e32 vcc, 16, v114
	v_sub_u32_e32 v112, 40, v113
	v_add_f32_e32 v83, v83, v119
	v_cndmask_b32_e32 v83, v115, v83, vcc
	s_waitcnt lgkmcnt(8)
	v_cmp_gt_u32_e32 vcc, 16, v112
	v_sub_u32_e32 v114, 41, v113
	v_add_f32_e32 v84, v84, v120
	v_cndmask_b32_e32 v84, v115, v84, vcc
	v_cmp_gt_u32_e32 vcc, 16, v114
	v_sub_u32_e32 v112, 42, v113
	v_add_f32_e32 v85, v85, v121
	v_cndmask_b32_e32 v85, v115, v85, vcc
	v_cmp_gt_u32_e32 vcc, 16, v112
	v_sub_u32_e32 v114, 43, v113
	v_add_f32_e32 v86, v86, v122
	v_cndmask_b32_e32 v86, v115, v86, vcc
	v_cmp_gt_u32_e32 vcc, 16, v114
	v_sub_u32_e32 v112, 48, v113
	v_add_f32_e32 v87, v87, v123
	v_cndmask_b32_e32 v87, v115, v87, vcc
	s_waitcnt lgkmcnt(4)
	v_cmp_gt_u32_e32 vcc, 16, v112
	v_sub_u32_e32 v114, 49, v113
	v_add_f32_e32 v88, v88, v124
	v_cndmask_b32_e32 v88, v115, v88, vcc
	v_cmp_gt_u32_e32 vcc, 16, v114
	v_sub_u32_e32 v112, 50, v113
	v_add_f32_e32 v89, v89, v125
	v_cndmask_b32_e32 v89, v115, v89, vcc
	v_cmp_gt_u32_e32 vcc, 16, v112
	v_sub_u32_e32 v114, 51, v113
	v_add_f32_e32 v90, v90, v126
	v_cndmask_b32_e32 v90, v115, v90, vcc
	v_cmp_gt_u32_e32 vcc, 16, v114
	v_sub_u32_e32 v112, 56, v113
	v_add_f32_e32 v91, v91, v127
	v_cndmask_b32_e32 v91, v115, v91, vcc
	s_waitcnt lgkmcnt(0)
	v_cmp_gt_u32_e32 vcc, 16, v112
	v_sub_u32_e32 v114, 57, v113
	v_add_f32_e32 v92, v92, v128
	v_cndmask_b32_e32 v92, v115, v92, vcc
	v_cmp_gt_u32_e32 vcc, 16, v114
	v_sub_u32_e32 v112, 58, v113
	v_add_f32_e32 v93, v93, v129
	v_cndmask_b32_e32 v93, v115, v93, vcc
	v_cmp_gt_u32_e32 vcc, 16, v112
	v_sub_u32_e32 v114, 59, v113
	v_add_f32_e32 v94, v94, v130
	v_cndmask_b32_e32 v94, v115, v94, vcc
	v_cmp_gt_u32_e32 vcc, 16, v114
	s_nop 0
	v_add_f32_e32 v95, v95, v131
	v_cndmask_b32_e32 v95, v115, v95, vcc
	s_branch .LBB0_475
